# prompt attention K tile key-major in LDS with XOR-swizzled 16-B chunks: every K LDS-DMA instruction reads 1 KB contiguous (4 key rows) instead of 64 scattered 16-B pieces
# speedup vs baseline: 1.0104x; 1.0104x over previous
; #define LAS __attribute__((address_space(3)))
; DI unsigned lds_addr(const LAS void* p) { return (unsigned)__builtin_amdgcn_readfirstlane((int)(unsigned)(size_t)p); }
; DI void load_tile(LAS unsigned char* buf, const bf16* Kg, const bf16* Vg, int kv0, int wave, int lane) {
; #pragma unroll
;     for (int i = 0; i < 2; ++i) { const int c = 2 * wave + i;
;         glds16(Kg + (size_t)(kv0 + lane) * 128 + c * 8, lds_addr(buf + c * 1024)); }
; #pragma unroll
;     for (int i = 0; i < 2; ++i) { const int pc = 2 * wave + i;
;         glds16(Vg + (size_t)(kv0 + 16 * (pc & 3) + (lane >> 2)) * 128 + (pc >> 2) * 32 + (lane & 3) * 8, lds_addr(buf + KT + (pc >> 2) * 4096 + (pc & 3) * 1024)); }
; }
; DI void attn_unit(Ctx A_, LAS unsigned char* lds, int b, int h, int qb, float lam, int wave, int lane) {
;     const int r = lane & 31, hh = lane >> 5, mp = wave >> 2, rg = wave & 3;
;     bf16* P = P_;
;     const size_t rowb = (size_t)b * SEQ;
;     const bf16* Kg = KC_ + (size_t)(b * 8 + h) * SEQ * 128; const bf16* Vg = VC_ + (size_t)(b * 8 + h) * SEQ * 128;
;     const int q0 = qb * 128 + rg * 32;
;     const int NT = 2 * qb + 2, NTw = 2 * qb + 1 + (rg >> 1);
;     LAS float* wsf = (LAS float*)(lds + WSF_OFF) + wave * 128;
;     bf16x8 qr[4];
;     { const bf16* Qg = P + (rowb + q0 + r) * PLD + C_QA + h * 128 + mp * 64 + hh * 8;
; #pragma unroll
;       for (int d0 = 0; d0 < 4; ++d0) qr[d0] = *(const bf16x8*)(Qg + d0 * 16); }
;     load_tile(lds, Kg, Vg, 0, wave, lane);
;     load_tile(lds + BUF, Kg, Vg, 64, wave, lane);
;     asm volatile("" : "+v"(qr[0]), "+v"(qr[1]), "+v"(qr[2]), "+v"(qr[3]));
;     f32x16 o[4];
; #pragma unroll
;     for (int nb = 0; nb < 4; ++nb)
; #pragma unroll
;         for (int i = 0; i < 16; ++i) o[nb][i] = 0.f;
;     float m = 0.f, l = 0.f;
;     const int g16 = (lane >> 4) & 1, p4 = lane & 3, q4 = (lane & 15) >> 2;
;     f32x16 negm;
; #pragma unroll
;     for (int i = 0; i < 16; ++i) negm[i] = 0.f;
;     bf16x8 kfa[4];
;     bf16x8 pfc[4];
; #pragma unroll
;     for (int i = 0; i < 4; ++i) pfc[i] = (bf16x8){0, 0, 0, 0, 0, 0, 0, 0};
;     const int vfo = KT + g16 * 32 + p4 * 8 + (4 * hh + q4) * 64;
.LBB0_868:
	s_or_b64 exec, exec, s[0:1]
	s_lshl_b32 s0, s8, 2
	s_add_i32 s0, s0, 0
	s_add_i32 s0, s0, 0x20040
	v_mov_b32_e32 v2, s0
	s_waitcnt lgkmcnt(0)
	s_barrier
	ds_read_b32 v2, v2
	s_mov_b64 s[0:1], -1
	s_waitcnt lgkmcnt(0)
	v_readfirstlane_b32 s4, v2
	s_cmpk_gt_i32 s4, 0x7ff
	s_cbranch_scc1 .LBB0_863
	s_ashr_i32 s6, s4, 8
	s_andn2_b32 s22, 31, s4
	s_ashr_i32 s7, s6, 31
	s_bfe_u32 s63, s4, 0x30005
	s_lshl_b64 s[0:1], s[6:7], 12
	s_lshl_b32 s4, s6, 3
	s_lshl_b32 s6, s22, 7
	v_readlane_b32 s7, v255, 28
	v_mov_b32 v10, v0
	s_or_b32 s64, s6, s7
	v_and_b32_e32 v196, 31, v10
	v_readlane_b32 s6, v255, 9
	v_or_b32_e32 v2, s64, v196
	v_readlane_b32 s7, v255, 10
	v_or_b32_e32 v4, s0, v2
	s_lshl_b32 s14, s63, 8
	v_mov_b64_e32 v[2:3], s[6:7]
	v_mad_u64_u32 v[2:3], s[6:7], v4, s57, v[2:3]
	v_mad_i32_i24 v3, s1, v213, v3
	v_bfe_u32 v197, v10, 5, 1
	v_lshl_add_u64 v[2:3], v[2:3], 0, s[14:15]
	v_lshl_add_u64 v[2:3], s[10:11], 1, v[2:3]
	v_lshlrev_b32_e32 v194, 4, v197
	v_lshl_add_u64 v[4:5], v[2:3], 0, v[194:195]
	global_load_dwordx4 v[146:149], v[4:5], off offset:96
	global_load_dwordx4 v[150:153], v[4:5], off offset:64
	global_load_dwordx4 v[154:157], v[4:5], off offset:32
	global_load_dwordx4 v[158:161], v[4:5], off
	s_or_b32 s4, s4, s63
	s_ashr_i32 s5, s4, 31
	s_lshl_b32 s65, s22, 1
	s_lshl_b64 s[4:5], s[4:5], 20
	v_and_b32_e32 v214, 63, v10
	s_add_u32 s6, s25, s4
	s_addc_u32 s7, s26, s5
	v_lshrrev_b32_e32 v8, 4, v214
	s_bfe_u32 s14, s33, 0x1000b
	s_lshl_b32 s14, s14, 3
	v_or_b32_e32 v9, s14, v8
	v_and_b32_e32 v2, 15, v214
	v_xor_b32_e32 v2, v2, v9
	v_lshlrev_b32_e32 v2, 4, v2
	v_lshl_or_b32 v2, v8, 8, v2
	v_add_u32_e32 v2, s33, v2
	v_and_b32_e32 v252, 64, v2
	v_lshlrev_b32_e32 v252, 1, v252
	v_sub_u32_e32 v252, 0x440, v252
	v_mov_b32_e32 v253, 0
	v_mov_b32_e32 v3, v195
	v_lshl_add_u64 v[6:7], s[6:7], 0, v[2:3]
	s_mov_b64 s[6:7], 0
	v_lshl_add_u64 v[8:9], v[6:7], 0, s[6:7]
	s_mov_b32 s8, m0
	s_mov_b32 m0, s37
	s_nop 0
	global_load_lds_dwordx4 v[8:9], off
	s_mov_b32 m0, s8
	s_lshl_b64 s[8:9], s[16:17], 1
	s_or_b32 s1, s24, s65
	v_lshl_add_u64 v[4:5], v[6:7], 0, v[252:253]
	s_add_i32 s1, s1, 1
	s_mov_b32 s14, m0
	s_mov_b32 m0, s39
	s_nop 0
	global_load_lds_dwordx4 v[4:5], off
	s_mov_b32 m0, s14
	v_lshlrev_b32_e32 v4, 3, v10
	v_bfe_u32 v11, v10, 2, 4
	s_add_u32 s66, s28, s4
	v_and_b32_e32 v12, 24, v4
	s_addc_u32 s67, s29, s5
	v_lshlrev_b32_e32 v4, 1, v12
	v_mov_b32_e32 v5, v195
	v_or_b32_e32 v8, s31, v11
	v_lshl_add_u64 v[4:5], s[66:67], 0, v[4:5]
	v_lshlrev_b32_e32 v8, 8, v8
	v_mov_b32_e32 v9, v195
	v_lshl_add_u64 v[8:9], v[4:5], 0, v[8:9]
	s_mov_b32 s14, m0
	s_mov_b32 m0, s35
	s_nop 0
	global_load_lds_dwordx4 v[8:9], off
	s_mov_b32 m0, s14
	v_or_b32_e32 v8, s42, v11
	v_lshlrev_b32_e32 v8, 8, v8
	v_mov_b32_e32 v9, v195
	v_lshl_add_u64 v[8:9], v[4:5], 0, v[8:9]
	v_lshl_add_u64 v[6:7], v[6:7], 0, s[18:19]
	s_mov_b32 s14, m0
	s_mov_b32 m0, s44
	s_nop 0
	global_load_lds_dwordx4 v[8:9], off
	s_mov_b32 m0, s14
	v_lshl_add_u64 v[8:9], v[6:7], 0, s[6:7]
	s_mov_b32 s6, m0
	s_mov_b32 m0, s45
	s_nop 0
	global_load_lds_dwordx4 v[8:9], off
	s_mov_b32 m0, s6
	v_lshl_add_u64 v[6:7], v[6:7], 0, v[252:253]
	v_or_b32_e32 v8, 64, v11
	s_mov_b32 s6, m0
	s_mov_b32 m0, s46
	s_nop 0
	global_load_lds_dwordx4 v[6:7], off
	s_mov_b32 m0, s6
	v_or_b32_e32 v6, s31, v8
	v_lshlrev_b32_e32 v6, 8, v6
	v_mov_b32_e32 v7, v195
	v_lshl_add_u64 v[6:7], v[4:5], 0, v[6:7]
	s_mov_b32 s6, m0
	s_mov_b32 m0, s47
	s_nop 0
	global_load_lds_dwordx4 v[6:7], off
	s_mov_b32 m0, s6
	v_or_b32_e32 v6, s42, v8
	v_lshlrev_b32_e32 v6, 8, v6
	v_mov_b32_e32 v7, v195
	v_lshl_add_u64 v[6:7], v[4:5], 0, v[6:7]
	s_mov_b32 s6, m0
	s_mov_b32 m0, s48
	s_nop 0
	global_load_lds_dwordx4 v[6:7], off
	s_mov_b32 m0, s6
	v_lshlrev_b32_e32 v6, 1, v10
	v_and_b32_e32 v6, 32, v6
	v_lshlrev_b32_e32 v8, 4, v10
	v_lshlrev_b32_e32 v7, 8, v197
	v_and_b32_e32 v8, 0xc0, v8
	v_add3_u32 v6, 0, v6, v12
	v_add3_u32 v215, v6, v7, v8
	v_lshlrev_b32_e32 v6, 10, v197
	v_lshlrev_b32_e32 v7, 4, v196
	v_mov_b32_e32 v6, s49
	v_lshrrev_b32_e32 v6, 10, v6
	v_or_b32_e32 v6, v6, v197
	v_and_b32_e32 v7, 15, v196
	v_xor_b32_e32 v6, v6, v7
	v_lshlrev_b32_e32 v6, 4, v6
	v_lshl_or_b32 v216, v196, 8, v6
	v_add_lshl_u32 v6, s53, v11, 8
	v_mov_b32_e32 v7, v195
	s_add_u32 s4, s55, s4
	s_waitcnt vmcnt(5)
	v_lshl_add_u64 v[198:199], v[4:5], 0, v[6:7]
	v_add_lshl_u32 v6, s54, v11, 8
	s_addc_u32 s5, s56, s5
	v_mov_b32_e32 v34, v195
	v_mov_b32_e32 v35, v195
	v_mov_b32_e32 v48, v195
	v_mov_b32_e32 v49, v195
	v_lshl_add_u64 v[200:201], v[4:5], 0, v[6:7]
	v_lshl_add_u64 v[202:203], s[4:5], 0, v[2:3]
	s_lshl_b32 s14, s22, 16
	v_mov_b32_e32 v36, v195
	v_mov_b32_e32 v37, v195
	v_mov_b32_e32 v38, v195
	v_mov_b32_e32 v39, v195
	v_mov_b32_e32 v40, v195
	v_mov_b32_e32 v41, v195
	v_mov_b32_e32 v42, v195
	v_mov_b32_e32 v43, v195
	v_mov_b32_e32 v44, v195
	v_mov_b32_e32 v45, v195
	v_mov_b32_e32 v46, v195
	v_mov_b32_e32 v47, v195
	s_waitcnt vmcnt(4)
	v_mov_b32_e32 v190, 0
	v_mov_b32_e32 v218, 0
	v_mov_b64_e32 v[64:65], v[48:49]
	v_mov_b64_e32 v[18:19], v[34:35]
	v_mov_b64_e32 v[2:3], v[34:35]
	v_cmp_gt_u32_e64 s[8:9], 32, v214
	v_lshl_add_u32 v217, v196, 2, s40
	s_add_i32 s14, s14, 0x18000
	s_mov_b32 s66, 0
	v_mov_b64_e32 v[62:63], v[46:47]
	v_mov_b64_e32 v[60:61], v[44:45]
	v_mov_b64_e32 v[58:59], v[42:43]
	v_mov_b64_e32 v[56:57], v[40:41]
	v_mov_b64_e32 v[54:55], v[38:39]
	v_mov_b64_e32 v[52:53], v[36:37]
	v_mov_b64_e32 v[50:51], v[34:35]
	v_mov_b64_e32 v[20:21], v[36:37]
	v_mov_b64_e32 v[22:23], v[38:39]
	v_mov_b64_e32 v[24:25], v[40:41]
	v_mov_b64_e32 v[26:27], v[42:43]
	v_mov_b64_e32 v[28:29], v[44:45]
	v_mov_b64_e32 v[30:31], v[46:47]
	v_mov_b64_e32 v[32:33], v[48:49]
	v_mov_b64_e32 v[4:5], v[36:37]
	v_mov_b64_e32 v[6:7], v[38:39]
	v_mov_b64_e32 v[8:9], v[40:41]
	v_mov_b64_e32 v[10:11], v[42:43]
	v_mov_b64_e32 v[12:13], v[44:45]
	v_mov_b64_e32 v[14:15], v[46:47]
	v_mov_b64_e32 v[16:17], v[48:49]
	v_mov_b32_e32 v219, 0
	s_mov_b32 s67, 0
	v_mov_b32_e32 v191, v190
	v_mov_b32_e32 v192, v190
	v_mov_b32_e32 v193, v190
	v_mov_b32_e32 v170, v190
	v_mov_b32_e32 v171, v190
	v_mov_b32_e32 v172, v190
	v_mov_b32_e32 v173, v190
	v_mov_b32_e32 v166, v190
	v_mov_b32_e32 v167, v190
	v_mov_b32_e32 v168, v190
	v_mov_b32_e32 v169, v190
	v_mov_b32_e32 v162, v190
	v_mov_b32_e32 v163, v190
	v_mov_b32_e32 v164, v190
	v_mov_b32_e32 v165, v190
	v_mov_b32_e32 v66, 0
	v_mov_b32_e32 v67, v218
	v_mov_b32_e32 v68, v218
	v_mov_b32_e32 v69, v218
	v_mov_b32_e32 v70, v218
	v_mov_b32_e32 v71, v218
	v_mov_b32_e32 v72, v218
	v_mov_b32_e32 v73, v218
	v_mov_b32_e32 v74, v218
	v_mov_b32_e32 v75, v218
	v_mov_b32_e32 v76, v218
	v_mov_b32_e32 v77, v218
	v_mov_b32_e32 v78, v218
	v_mov_b32_e32 v79, v218
	v_mov_b32_e32 v80, v218
	v_mov_b32_e32 v81, v218
	s_waitcnt vmcnt(0)
	s_branch .LBB0_872

; #define LAS __attribute__((address_space(3)))
; DI unsigned lds_addr(const LAS void* p) { return (unsigned)__builtin_amdgcn_readfirstlane((int)(unsigned)(size_t)p); }
; DI void load_tile(LAS unsigned char* buf, const bf16* Kg, const bf16* Vg, int kv0, int wave, int lane) {
; #pragma unroll
;     for (int i = 0; i < 2; ++i) { const int c = 2 * wave + i;
;         glds16(Kg + (size_t)(kv0 + lane) * 128 + c * 8, lds_addr(buf + c * 1024)); }
; #pragma unroll
;     for (int i = 0; i < 2; ++i) { const int pc = 2 * wave + i;
;         glds16(Vg + (size_t)(kv0 + 16 * (pc & 3) + (lane >> 2)) * 128 + (pc >> 2) * 32 + (lane & 3) * 8, lds_addr(buf + KT + (pc >> 2) * 4096 + (pc & 3) * 1024)); }
; }
; DI void attn_unit(Ctx A_, LAS unsigned char* lds, int b, int h, int qb, float lam, int wave, int lane) {
;     ...
;     for (int t = 0; t <= NT; ++t) {
;         asm volatile("s_waitcnt vmcnt(0) lgkmcnt(0)" ::: "memory");
;         __builtin_amdgcn_s_barrier(); asm volatile("" ::: "memory");
;         if (t + 2 < NT) load_tile(lds + ((t + 2) & 3) * BUF, Kg, Vg, (t + 2) * 64, wave, lane);
.LBB0_872:
	s_waitcnt vmcnt(0) lgkmcnt(0)
	s_barrier
	s_cmp_ge_u32 s67, s65
	s_cbranch_scc1 .LBB0_874
	s_add_i32 s4, s66, 0x10000
	s_and_b32 s4, s4, 0x18000
	s_add_i32 s4, s4, 0
	s_add_i32 s5, s4, s33
	v_mov_b64_e32 v[82:83], v[202:203]
	s_mov_b32 s6, m0
	s_mov_b32 m0, s5
	s_nop 0
	global_load_lds_dwordx4 v[82:83], off
	s_mov_b32 m0, s6
	s_add_i32 s5, s4, s38
	s_add_i32 s4, s4, s30
	v_lshl_add_u64 v[82:83], v[202:203], 0, v[252:253]
	s_mov_b32 s6, m0
	s_mov_b32 m0, s5
	s_nop 0
	global_load_lds_dwordx4 v[82:83], off
	s_mov_b32 m0, s6
	s_add_i32 s5, s4, s34
	s_addk_i32 s5, 0x4000
	s_mov_b32 s6, m0
	s_mov_b32 m0, s5
	s_nop 0
	global_load_lds_dwordx4 v[200:201], off
	s_mov_b32 m0, s6
	s_add_i32 s4, s4, s43
	s_addk_i32 s4, 0x4000
	s_mov_b32 s5, m0
	s_mov_b32 m0, s4
	s_nop 0
	global_load_lds_dwordx4 v[198:199], off
	s_mov_b32 m0, s5

; #define LAS __attribute__((address_space(3)))
; #define LOADV(f, ks) _Pragma("unroll") for (int nb = 0; nb < 4; ++nb) { const s16x4 lo = vtr(vp + nb * 4096 + (ks) * 1024), hi = vtr(vp + nb * 4096 + (ks) * 1024 + 512); f[nb] = __builtin_shufflevector(lo, hi, 0, 1, 2, 3, 4, 5, 6, 7); }
; DI void attn_unit(Ctx A_, LAS unsigned char* lds, int b, int h, int qb, float lam, int wave, int lane) {
;     ...
;         if (has_s) {
;             const LAS unsigned char* kb = lds + (t & 3) * BUF + (mp * 8 + hh) * 1024 + r * 16;
;             const bool first = t == 0;
;             const float mi = first ? 0.f : m;
;             f32x16 p0, p1;
;             bf16x8 fa4[4], fb4[4];
;             { bf16x8 kf[8];
;               if (first) {
; #pragma unroll
;                   for (int d0 = 0; d0 < 2; ++d0) { kfa[2 * d0] = *(const LAS bf16x8*)(kb + d0 * 2048); kfa[2 * d0 + 1] = *(const LAS bf16x8*)(kb + d0 * 2048 + 512); }
;               }
; #pragma unroll
;               for (int d0 = 2; d0 < 4; ++d0) { kf[2 * d0] = *(const LAS bf16x8*)(kb + d0 * 2048); kf[2 * d0 + 1] = *(const LAS bf16x8*)(kb + d0 * 2048 + 512); }
; #pragma unroll
;               for (int i = 0; i < 4; ++i) kf[i] = kfa[i];
;               LOADV(fa4, 0) LOADV(fb4, 1)
;               __builtin_amdgcn_sched_barrier(0);
;               __builtin_amdgcn_s_setprio(1);
; #pragma unroll
;               for (int d0 = 0; d0 < 4; ++d0) {
;                   p0 = __builtin_amdgcn_mfma_f32_32x32x16_bf16(kf[2 * d0], qr[d0], d0 == 0 ? negm : p0, 0, 0, 0);
;                   p1 = __builtin_amdgcn_mfma_f32_32x32x16_bf16(kf[2 * d0 + 1], qr[d0], d0 == 0 ? negm : p1, 0, 0, 0);
;               }
;               __builtin_amdgcn_s_setprio(0);
;               __builtin_amdgcn_sched_barrier(0); }
;     ...
;             float ta = MX3(p0[0], p0[1], p1[0]), tb2 = MX3(p0[2], p0[3], p1[1]); ta = MX3(ta, p1[2], p1[3]);
; #pragma unroll
;             for (int i = 4; i < 16; i += 4) { ta = MX3(ta, p0[i], p0[i + 1]); tb2 = MX3(tb2, p0[i + 2], p0[i + 3]); ta = MX3(ta, p1[i], p1[i + 1]); tb2 = MX3(tb2, p1[i + 2], p1[i + 3]); }
;     ...
;             float tm = fmaxf(ta, tb2);
;             { const auto rr = __builtin_amdgcn_permlane32_swap(__float_as_uint(tm), __float_as_uint(tm), false, false); tm = fmaxf(__uint_as_float(rr[0]), __uint_as_float(rr[1])); }
;             const bool resc = first || __any(tm > RESC_THR);
.LBB0_878:
	s_and_b32 s22, s66, 0x18000
	s_andn2_b64 vcc, exec, s[4:5]
	v_add_u32_e32 v82, s22, v216
	v_xor_b32_e32 v83, 32, v82
	v_xor_b32_e32 v84, 64, v82
	v_xor_b32_e32 v85, 0x60, v82
	s_cbranch_vccnz .LBB0_880
	s_waitcnt lgkmcnt(3)
	ds_read_b128 v[174:177], v82
	s_waitcnt lgkmcnt(3)
	ds_read_b128 v[178:181], v82 offset:8192
	s_waitcnt lgkmcnt(3)
	ds_read_b128 v[182:185], v83
	s_waitcnt lgkmcnt(3)
	ds_read_b128 v[186:189], v83 offset:8192
.LBB0_880:
	ds_read_b128 v[222:225], v84
	ds_read_b128 v[226:229], v84 offset:8192
	ds_read_b128 v[230:233], v85
	ds_read_b128 v[234:237], v85 offset:8192
	ds_read_b64_tr_b16 v[134:135], v220 offset:16384
	ds_read_b64_tr_b16 v[136:137], v220 offset:16896
	ds_read_b64_tr_b16 v[126:127], v220 offset:17408
	ds_read_b64_tr_b16 v[128:129], v220 offset:17920
	ds_read_b64_tr_b16 v[142:143], v220 offset:20480
	ds_read_b64_tr_b16 v[144:145], v220 offset:20992
	ds_read_b64_tr_b16 v[122:123], v220 offset:21504
	ds_read_b64_tr_b16 v[124:125], v220 offset:22016
	ds_read_b64_tr_b16 v[138:139], v220 offset:24576
	ds_read_b64_tr_b16 v[140:141], v220 offset:25088
	ds_read_b64_tr_b16 v[118:119], v220 offset:25600
	ds_read_b64_tr_b16 v[120:121], v220 offset:26112
	ds_read_b64_tr_b16 v[130:131], v220 offset:28672
	ds_read_b64_tr_b16 v[132:133], v220 offset:29184
	ds_read_b64_tr_b16 v[114:115], v220 offset:29696
	ds_read_b64_tr_b16 v[116:117], v220 offset:30208
	s_setprio 1
	s_waitcnt lgkmcnt(14)
	v_mfma_f32_32x32x16_bf16 v[98:113], v[174:177], v[158:161], v[66:81]
	v_mfma_f32_32x32x16_bf16 v[82:97], v[178:181], v[158:161], v[66:81]
	v_mfma_f32_32x32x16_bf16 v[98:113], v[182:185], v[154:157], v[98:113]
	v_mfma_f32_32x32x16_bf16 v[82:97], v[186:189], v[154:157], v[82:97]
	v_mfma_f32_32x32x16_bf16 v[98:113], v[222:225], v[150:153], v[98:113]
	v_mfma_f32_32x32x16_bf16 v[82:97], v[226:229], v[150:153], v[82:97]
	v_mfma_f32_32x32x16_bf16 v[98:113], v[230:233], v[146:149], v[98:113]
	v_mfma_f32_32x32x16_bf16 v[82:97], v[234:237], v[146:149], v[82:97]
	s_setprio 0
	s_nop 9
	v_max_f32_e32 v174, v99, v99
	v_max_f32_e32 v175, v98, v98
	v_max_f32_e32 v174, v175, v174
	v_max3_f32 v175, v100, v101, v83
	v_max3_f32 v174, v174, v82, v84
	v_max3_f32 v174, v174, v85, v102
	v_max3_f32 v175, v175, v104, v105
	v_max3_f32 v174, v174, v103, v86
	v_max3_f32 v175, v175, v88, v89
	v_max3_f32 v174, v174, v87, v106
	v_max3_f32 v175, v175, v108, v109
	v_max3_f32 v174, v174, v107, v90
	v_max3_f32 v175, v175, v92, v93
	v_max3_f32 v174, v174, v91, v110
	v_max3_f32 v175, v175, v112, v113
	v_max3_f32 v174, v174, v111, v94
	v_max3_f32 v175, v175, v96, v97
	v_max3_f32 v174, v174, v95, v175
	v_mov_b32_e32 v175, v174
	s_nop 1
	v_permlane32_swap_b32_e32 v174, v175
	v_max_f32_e32 v175, v175, v175
	v_max_f32_e32 v174, v174, v174
	v_max_f32_e32 v174, v174, v175
	s_andn2_b64 vcc, exec, s[6:7]
	s_mov_b64 s[22:23], -1
	s_cbranch_vccnz .LBB0_882
	s_mov_b32 s6, 0x41000000
	v_cmp_lt_f32_e32 vcc, s6, v174
	s_cmp_lg_u64 vcc, 0
	s_cselect_b64 s[22:23], -1, 0

; #define LAS __attribute__((address_space(3)))
; DI int crow(int i, int hh) { return (i & 3) + 8 * (i >> 2) + 4 * hh; }
; #define LOADV(f, ks) _Pragma("unroll") for (int nb = 0; nb < 4; ++nb) { const s16x4 lo = vtr(vp + nb * 4096 + (ks) * 1024), hi = vtr(vp + nb * 4096 + (ks) * 1024 + 512); f[nb] = __builtin_shufflevector(lo, hi, 0, 1, 2, 3, 4, 5, 6, 7); }
; #define SB __builtin_amdgcn_sched_barrier(0);
; #define GRP(P, i, f, ks, nb) { ls += qa_ + qb_; float ea_, eb_; asm volatile("v_exp_f32 %0, %2\n\tv_exp_f32 %1, %3" : "=&v"(ea_), "=&v"(eb_) : "v"(P[i]), "v"(P[(i) + 1])); P[i] = ea_; P[(i) + 1] = eb_; qa_ = ea_; qb_ = eb_; \
;                   o[nb] = __builtin_amdgcn_mfma_f32_32x32x16_bf16(pfc[ks], f[nb], o[nb], 0, 0, 0); SB }
; DI void attn_unit(Ctx A_, LAS unsigned char* lds, int b, int h, int qb, float lam, int wave, int lane) {
;     ...
;               SB __builtin_amdgcn_s_setprio(1); SB
;               GRP(p0, 0, fa4, 0, 0) GRP(p0, 2, fa4, 0, 1) GRP(p0, 4, fa4, 0, 2) GRP(p0, 6, fa4, 0, 3)
;               LOADV(fa4, 2) SB
;               pfn[0] = pack8(p0, 0);
;               GRP(p0, 8, fb4, 1, 0) GRP(p0, 10, fb4, 1, 1) GRP(p0, 12, fb4, 1, 2) GRP(p0, 14, fb4, 1, 3)
;               LOADV(fb4, 3) SB
;               { const LAS unsigned char* kn = lds + ((t + 1) & 3) * BUF + (mp * 8 + hh) * 1024 + r * 16;
; #pragma unroll
;                 for (int d0 = 0; d0 < 2; ++d0) { kfa[2 * d0] = *(const LAS bf16x8*)(kn + d0 * 2048); kfa[2 * d0 + 1] = *(const LAS bf16x8*)(kn + d0 * 2048 + 512); } }
;               SB
;               pfn[1] = pack8(p0, 8);
;               GRP(p1, 0, fa4, 2, 0) GRP(p1, 2, fa4, 2, 1) GRP(p1, 4, fa4, 2, 2) GRP(p1, 6, fa4, 2, 3)
;               pfn[2] = pack8(p1, 0);
;               GRP(p1, 8, fb4, 3, 0) GRP(p1, 10, fb4, 3, 1) GRP(p1, 12, fb4, 3, 2) GRP(p1, 14, fb4, 3, 3)
;               __builtin_amdgcn_s_setprio(0); SB
;               ls += qa_ + qb_; pfn[3] = pack8(p1, 8);
;     ...
;             }
;             l += ls;
; #pragma unroll
;             for (int i = 0; i < 4; ++i) pfc[i] = pfn[i];
;             if (resc) {
;                 float fr[16];
; #pragma unroll
;                 for (int i = 0; i < 16; ++i) fr[i] = wsf[crow(i, hh)];
; #pragma unroll
;                 for (int nb = 0; nb < 4; ++nb)
; #pragma unroll
;                     for (int i = 0; i < 16; ++i) o[nb][i] *= fr[i];
.LBB0_886:
	s_setprio 1
	v_mfma_f32_32x32x16_bf16 v[34:49], v[190:193], v[134:137], v[34:49]
	v_exp_f32 v221, v98
	v_exp_f32 v222, v99
	s_waitcnt lgkmcnt(10)
	v_mfma_f32_32x32x16_bf16 v[50:65], v[190:193], v[142:145], v[50:65]
	v_exp_f32 v134, v100
	v_exp_f32 v135, v101
	s_waitcnt lgkmcnt(6)
	v_mfma_f32_32x32x16_bf16 v[18:33], v[190:193], v[138:141], v[18:33]
	v_exp_f32 v136, v102
	v_exp_f32 v137, v103
	s_waitcnt lgkmcnt(2)
	v_mfma_f32_32x32x16_bf16 v[2:17], v[190:193], v[130:133], v[2:17]
	v_exp_f32 v138, v104
	v_exp_f32 v139, v105
	ds_read_b64_tr_b16 v[130:131], v220 offset:18432
	ds_read_b64_tr_b16 v[132:133], v220 offset:18944
	ds_read_b64_tr_b16 v[140:141], v220 offset:22528
	ds_read_b64_tr_b16 v[142:143], v220 offset:23040
	ds_read_b64_tr_b16 v[190:191], v220 offset:26624
	ds_read_b64_tr_b16 v[192:193], v220 offset:27136
	ds_read_b64_tr_b16 v[224:225], v220 offset:30720
	ds_read_b64_tr_b16 v[226:227], v220 offset:31232
	v_mfma_f32_32x32x16_bf16 v[34:49], v[170:173], v[126:129], v[34:49]
	v_exp_f32 v100, v106
	v_exp_f32 v98, v107
	v_mfma_f32_32x32x16_bf16 v[50:65], v[170:173], v[122:125], v[50:65]
	v_exp_f32 v101, v108
	v_exp_f32 v99, v109
	v_mfma_f32_32x32x16_bf16 v[18:33], v[170:173], v[118:121], v[18:33]
	v_exp_f32 v104, v110
	v_exp_f32 v102, v111
	s_waitcnt lgkmcnt(8)
	v_mfma_f32_32x32x16_bf16 v[2:17], v[170:173], v[114:117], v[2:17]
	v_exp_f32 v105, v112
	v_exp_f32 v103, v113
	ds_read_b64_tr_b16 v[114:115], v220 offset:19456
	ds_read_b64_tr_b16 v[116:117], v220 offset:19968
	ds_read_b64_tr_b16 v[118:119], v220 offset:23552
	ds_read_b64_tr_b16 v[120:121], v220 offset:24064
	ds_read_b64_tr_b16 v[122:123], v220 offset:27648
	ds_read_b64_tr_b16 v[124:125], v220 offset:28160
	ds_read_b64_tr_b16 v[126:127], v220 offset:31744
	ds_read_b64_tr_b16 v[128:129], v220 offset:32256
	s_add_i32 s4, s66, 0x8000
	s_and_b32 s4, s4, 0x18000
	v_add_u32_e32 v106, s4, v216
	v_xor_b32_e32 v107, 32, v106
	ds_read_b128 v[174:177], v106
	ds_read_b128 v[178:181], v106 offset:8192
	ds_read_b128 v[182:185], v107
	ds_read_b128 v[186:189], v107 offset:8192
	s_waitcnt lgkmcnt(14)
	v_mfma_f32_32x32x16_bf16 v[34:49], v[166:169], v[130:133], v[34:49]
	v_exp_f32 v108, v82
	v_exp_f32 v106, v83
	v_mfma_f32_32x32x16_bf16 v[50:65], v[166:169], v[140:143], v[50:65]
	v_exp_f32 v109, v84
	v_exp_f32 v107, v85
	v_mfma_f32_32x32x16_bf16 v[18:33], v[166:169], v[190:193], v[18:33]
	v_exp_f32 v112, v86
	v_exp_f32 v110, v87
	s_waitcnt lgkmcnt(12)
	v_mfma_f32_32x32x16_bf16 v[2:17], v[166:169], v[224:227], v[2:17]
	v_exp_f32 v113, v88
	v_exp_f32 v111, v89
	s_waitcnt lgkmcnt(10)
	v_mfma_f32_32x32x16_bf16 v[34:49], v[162:165], v[114:117], v[34:49]
	v_exp_f32 v84, v90
	v_exp_f32 v82, v91
	s_waitcnt lgkmcnt(8)
	v_mfma_f32_32x32x16_bf16 v[50:65], v[162:165], v[118:121], v[50:65]
	v_exp_f32 v85, v92
	v_exp_f32 v83, v93
	s_waitcnt lgkmcnt(6)
	v_mfma_f32_32x32x16_bf16 v[18:33], v[162:165], v[122:125], v[18:33]
	v_exp_f32 v88, v94
	v_exp_f32 v86, v95
	s_waitcnt lgkmcnt(4)
	v_mfma_f32_32x32x16_bf16 v[2:17], v[162:165], v[126:129], v[2:17]
	v_exp_f32 v89, v96
	v_exp_f32 v87, v97
	s_setprio 0
	s_and_b64 vcc, exec, s[6:7]
	s_cbranch_vccnz .LBB0_888
	v_add_u32_e32 v118, s40, v194
	ds_read_b128 v[90:93], v118 offset:96
	ds_read_b128 v[94:97], v118 offset:64
	ds_read_b128 v[114:117], v118 offset:32
	ds_read_b128 v[118:121], v118
	s_waitcnt lgkmcnt(3)
	v_pk_mul_f32 v[46:47], v[46:47], v[90:91]
	s_waitcnt lgkmcnt(2)
	v_pk_mul_f32 v[42:43], v[42:43], v[94:95]
	s_waitcnt lgkmcnt(1)
	v_pk_mul_f32 v[38:39], v[38:39], v[114:115]
	v_pk_mul_f32 v[48:49], v[48:49], v[92:93]
	v_pk_mul_f32 v[44:45], v[44:45], v[96:97]
	v_pk_mul_f32 v[40:41], v[40:41], v[116:117]
	s_waitcnt lgkmcnt(0)
	v_pk_mul_f32 v[36:37], v[36:37], v[120:121]
	v_pk_mul_f32 v[34:35], v[34:35], v[118:119]
	v_pk_mul_f32 v[62:63], v[62:63], v[90:91]
	v_pk_mul_f32 v[58:59], v[58:59], v[94:95]
	v_pk_mul_f32 v[54:55], v[54:55], v[114:115]
	v_pk_mul_f32 v[64:65], v[64:65], v[92:93]
	v_pk_mul_f32 v[60:61], v[60:61], v[96:97]
	v_pk_mul_f32 v[56:57], v[56:57], v[116:117]
	v_pk_mul_f32 v[52:53], v[52:53], v[120:121]
	v_pk_mul_f32 v[50:51], v[50:51], v[118:119]
	v_pk_mul_f32 v[30:31], v[30:31], v[90:91]
	v_pk_mul_f32 v[26:27], v[26:27], v[94:95]
	v_pk_mul_f32 v[22:23], v[22:23], v[114:115]
	v_pk_mul_f32 v[32:33], v[32:33], v[92:93]
	v_pk_mul_f32 v[28:29], v[28:29], v[96:97]
	v_pk_mul_f32 v[24:25], v[24:25], v[116:117]
	v_pk_mul_f32 v[20:21], v[20:21], v[120:121]
	v_pk_mul_f32 v[18:19], v[18:19], v[118:119]
	v_pk_mul_f32 v[14:15], v[14:15], v[90:91]
	v_pk_mul_f32 v[10:11], v[10:11], v[94:95]
	v_pk_mul_f32 v[6:7], v[6:7], v[114:115]
	v_pk_mul_f32 v[16:17], v[16:17], v[92:93]
	v_pk_mul_f32 v[12:13], v[12:13], v[96:97]
	v_pk_mul_f32 v[8:9], v[8:9], v[116:117]
	v_pk_mul_f32 v[4:5], v[4:5], v[120:121]
	v_pk_mul_f32 v[2:3], v[2:3], v[118:119]
